# adds runtime placement check + fallback for the XCD-local barriers, and P0 w16 fill with batched loads
# baseline (speedup 1.0000x reference)
.LBB0_6:
	s_waitcnt lgkmcnt(0)
	s_barrier
	s_add_u32 s14, s92, 0x510000
	s_getreg_b32 s3, hwreg(HW_REG_XCC_ID, 0, 4)
	s_addc_u32 s15, s93, 0
	s_and_b32 s3, s3, 15
	v_readfirstlane_b32 s6, v194
	s_cmp_gt_u32 s6, 63
	s_cbranch_scc1 .LBB0_11
	v_mbcnt_lo_u32_b32 v1, -1, 0
	v_mbcnt_hi_u32_b32 v1, -1, v1
	s_nop 0
	v_cmp_eq_u32_e32 vcc, 0, v1
	s_and_saveexec_b64 s[6:7], vcc
	s_cbranch_execz .LBB0_10
	s_mov_b64 s[8:9], exec
	v_mbcnt_lo_u32_b32 v1, s8, 0
	v_mbcnt_hi_u32_b32 v1, s9, v1
	v_cmp_eq_u32_e32 vcc, 0, v1
	s_and_b64 s[10:11], exec, vcc
	s_mov_b64 exec, s[10:11]
	s_cbranch_execz .LBB0_10
	s_and_b32 s16, s2, 7
	s_lshl_b32 s16, s16, 8
	s_add_u32 s16, s16, 0x3600
	s_lshl_b32 s17, 1, s3
	v_mov_b32_e32 v4, s16
	v_mov_b32_e32 v5, s17
	global_atomic_or v4, v5, s[14:15]
	s_waitcnt vmcnt(0)
	s_lshl_b32 s10, s3, 8
	s_bcnt1_i32_b64 s8, s[8:9]
	v_mov_b32_e32 v1, s10
	v_mov_b32_e32 v2, s8
	global_atomic_add v1, v2, s[14:15] offset:1024

.LBB0_23:
	s_and_b32 s4, s33, 0xffffffc0
	v_mbcnt_lo_u32_b32 v32, -1, 0
	v_mbcnt_hi_u32_b32 v32, -1, v32
	v_writelane_b32 v242, s4, 8
	v_add_u32_e32 v0, s4, v32
	s_waitcnt lgkmcnt(0)
	v_and_b32_e32 v9, 15, v32
	v_lshrrev_b32_e32 v1, 4, v0
	v_mov_b32_e32 v2, 0x4040
	v_mul_u32_u24_e32 v2, v1, v2
	v_lshl_add_u32 v2, v9, 2, v2
	v_lshlrev_b32_e32 v4, 2, v1
	v_lshl_add_u32 v5, v9, 12, v4
	s_add_u32 s6, s78, 0x4000
	s_addc_u32 s7, s79, 0
	global_load_dword v40, v4, s[76:77] offset:0
	global_load_dword v72, v2, s[6:7]
	s_add_u32 s6, s6, 0x80800
	s_addc_u32 s7, s7, 0
	global_load_dword v41, v4, s[76:77] offset:128
	global_load_dword v73, v2, s[6:7]
	s_add_u32 s6, s6, 0x80800
	s_addc_u32 s7, s7, 0
	global_load_dword v42, v4, s[76:77] offset:256
	global_load_dword v74, v2, s[6:7]
	s_add_u32 s6, s6, 0x80800
	s_addc_u32 s7, s7, 0
	global_load_dword v43, v4, s[76:77] offset:384
	global_load_dword v75, v2, s[6:7]
	s_add_u32 s6, s6, 0x80800
	s_addc_u32 s7, s7, 0
	global_load_dword v44, v4, s[76:77] offset:512
	global_load_dword v76, v2, s[6:7]
	s_add_u32 s6, s6, 0x80800
	s_addc_u32 s7, s7, 0
	global_load_dword v45, v4, s[76:77] offset:640
	global_load_dword v77, v2, s[6:7]
	s_add_u32 s6, s6, 0x80800
	s_addc_u32 s7, s7, 0
	global_load_dword v46, v4, s[76:77] offset:768
	global_load_dword v78, v2, s[6:7]
	s_add_u32 s6, s6, 0x80800
	s_addc_u32 s7, s7, 0
	global_load_dword v47, v4, s[76:77] offset:896
	global_load_dword v79, v2, s[6:7]
	s_add_u32 s6, s6, 0x80800
	s_addc_u32 s7, s7, 0
	global_load_dword v48, v4, s[76:77] offset:1024
	global_load_dword v80, v2, s[6:7]
	s_add_u32 s6, s6, 0x80800
	s_addc_u32 s7, s7, 0
	global_load_dword v49, v4, s[76:77] offset:1152
	global_load_dword v81, v2, s[6:7]
	s_add_u32 s6, s6, 0x80800
	s_addc_u32 s7, s7, 0
	global_load_dword v50, v4, s[76:77] offset:1280
	global_load_dword v82, v2, s[6:7]
	s_add_u32 s6, s6, 0x80800
	s_addc_u32 s7, s7, 0
	global_load_dword v51, v4, s[76:77] offset:1408
	global_load_dword v83, v2, s[6:7]
	s_add_u32 s6, s6, 0x80800
	s_addc_u32 s7, s7, 0
	global_load_dword v52, v4, s[76:77] offset:1536
	global_load_dword v84, v2, s[6:7]
	s_add_u32 s6, s6, 0x80800
	s_addc_u32 s7, s7, 0
	global_load_dword v53, v4, s[76:77] offset:1664
	global_load_dword v85, v2, s[6:7]
	s_add_u32 s6, s6, 0x80800
	s_addc_u32 s7, s7, 0
	global_load_dword v54, v4, s[76:77] offset:1792
	global_load_dword v86, v2, s[6:7]
	s_add_u32 s6, s6, 0x80800
	s_addc_u32 s7, s7, 0
	global_load_dword v55, v4, s[76:77] offset:1920
	global_load_dword v87, v2, s[6:7]
	s_add_u32 s6, s6, 0x80800
	s_addc_u32 s7, s7, 0
	s_waitcnt vmcnt(30)
	v_mul_f32_e32 v40, v40, v72
	ds_write_b32 v5, v40 offset:0
	s_waitcnt vmcnt(28)
	v_mul_f32_e32 v41, v41, v73
	ds_write_b32 v5, v41 offset:128
	s_waitcnt vmcnt(26)
	v_mul_f32_e32 v42, v42, v74
	ds_write_b32 v5, v42 offset:256
	s_waitcnt vmcnt(24)
	v_mul_f32_e32 v43, v43, v75
	ds_write_b32 v5, v43 offset:384
	s_waitcnt vmcnt(22)
	v_mul_f32_e32 v44, v44, v76
	ds_write_b32 v5, v44 offset:512
	s_waitcnt vmcnt(20)
	v_mul_f32_e32 v45, v45, v77
	ds_write_b32 v5, v45 offset:640
	s_waitcnt vmcnt(18)
	v_mul_f32_e32 v46, v46, v78
	ds_write_b32 v5, v46 offset:768
	s_waitcnt vmcnt(16)
	v_mul_f32_e32 v47, v47, v79
	ds_write_b32 v5, v47 offset:896
	s_waitcnt vmcnt(14)
	v_mul_f32_e32 v48, v48, v80
	ds_write_b32 v5, v48 offset:1024
	s_waitcnt vmcnt(12)
	v_mul_f32_e32 v49, v49, v81
	ds_write_b32 v5, v49 offset:1152
	s_waitcnt vmcnt(10)
	v_mul_f32_e32 v50, v50, v82
	ds_write_b32 v5, v50 offset:1280
	s_waitcnt vmcnt(8)
	v_mul_f32_e32 v51, v51, v83
	ds_write_b32 v5, v51 offset:1408
	s_waitcnt vmcnt(6)
	v_mul_f32_e32 v52, v52, v84
	ds_write_b32 v5, v52 offset:1536
	s_waitcnt vmcnt(4)
	v_mul_f32_e32 v53, v53, v85
	ds_write_b32 v5, v53 offset:1664
	s_waitcnt vmcnt(2)
	v_mul_f32_e32 v54, v54, v86
	ds_write_b32 v5, v54 offset:1792
	s_waitcnt vmcnt(0)
	v_mul_f32_e32 v55, v55, v87
	ds_write_b32 v5, v55 offset:1920
	global_load_dword v40, v4, s[76:77] offset:2048
	global_load_dword v72, v2, s[6:7]
	s_add_u32 s6, s6, 0x80800
	s_addc_u32 s7, s7, 0
	global_load_dword v41, v4, s[76:77] offset:2176
	global_load_dword v73, v2, s[6:7]
	s_add_u32 s6, s6, 0x80800
	s_addc_u32 s7, s7, 0
	global_load_dword v42, v4, s[76:77] offset:2304
	global_load_dword v74, v2, s[6:7]
	s_add_u32 s6, s6, 0x80800
	s_addc_u32 s7, s7, 0
	global_load_dword v43, v4, s[76:77] offset:2432
	global_load_dword v75, v2, s[6:7]
	s_add_u32 s6, s6, 0x80800
	s_addc_u32 s7, s7, 0
	global_load_dword v44, v4, s[76:77] offset:2560
	global_load_dword v76, v2, s[6:7]
	s_add_u32 s6, s6, 0x80800
	s_addc_u32 s7, s7, 0
	global_load_dword v45, v4, s[76:77] offset:2688
	global_load_dword v77, v2, s[6:7]
	s_add_u32 s6, s6, 0x80800
	s_addc_u32 s7, s7, 0
	global_load_dword v46, v4, s[76:77] offset:2816
	global_load_dword v78, v2, s[6:7]
	s_add_u32 s6, s6, 0x80800
	s_addc_u32 s7, s7, 0
	global_load_dword v47, v4, s[76:77] offset:2944
	global_load_dword v79, v2, s[6:7]
	s_add_u32 s6, s6, 0x80800
	s_addc_u32 s7, s7, 0
	global_load_dword v48, v4, s[76:77] offset:3072
	global_load_dword v80, v2, s[6:7]
	s_add_u32 s6, s6, 0x80800
	s_addc_u32 s7, s7, 0
	global_load_dword v49, v4, s[76:77] offset:3200
	global_load_dword v81, v2, s[6:7]
	s_add_u32 s6, s6, 0x80800
	s_addc_u32 s7, s7, 0
	global_load_dword v50, v4, s[76:77] offset:3328
	global_load_dword v82, v2, s[6:7]
	s_add_u32 s6, s6, 0x80800
	s_addc_u32 s7, s7, 0
	global_load_dword v51, v4, s[76:77] offset:3456
	global_load_dword v83, v2, s[6:7]
	s_add_u32 s6, s6, 0x80800
	s_addc_u32 s7, s7, 0
	global_load_dword v52, v4, s[76:77] offset:3584
	global_load_dword v84, v2, s[6:7]
	s_add_u32 s6, s6, 0x80800
	s_addc_u32 s7, s7, 0
	global_load_dword v53, v4, s[76:77] offset:3712
	global_load_dword v85, v2, s[6:7]
	s_add_u32 s6, s6, 0x80800
	s_addc_u32 s7, s7, 0
	global_load_dword v54, v4, s[76:77] offset:3840
	global_load_dword v86, v2, s[6:7]
	s_add_u32 s6, s6, 0x80800
	s_addc_u32 s7, s7, 0
	global_load_dword v55, v4, s[76:77] offset:3968
	global_load_dword v87, v2, s[6:7]
	s_add_u32 s6, s6, 0x80800
	s_addc_u32 s7, s7, 0
	s_waitcnt vmcnt(30)
	v_mul_f32_e32 v40, v40, v72
	ds_write_b32 v5, v40 offset:2048
	s_waitcnt vmcnt(28)
	v_mul_f32_e32 v41, v41, v73
	ds_write_b32 v5, v41 offset:2176
	s_waitcnt vmcnt(26)
	v_mul_f32_e32 v42, v42, v74
	ds_write_b32 v5, v42 offset:2304
	s_waitcnt vmcnt(24)
	v_mul_f32_e32 v43, v43, v75
	ds_write_b32 v5, v43 offset:2432
	s_waitcnt vmcnt(22)
	v_mul_f32_e32 v44, v44, v76
	ds_write_b32 v5, v44 offset:2560
	s_waitcnt vmcnt(20)
	v_mul_f32_e32 v45, v45, v77
	ds_write_b32 v5, v45 offset:2688
	s_waitcnt vmcnt(18)
	v_mul_f32_e32 v46, v46, v78
	ds_write_b32 v5, v46 offset:2816
	s_waitcnt vmcnt(16)
	v_mul_f32_e32 v47, v47, v79
	ds_write_b32 v5, v47 offset:2944
	s_waitcnt vmcnt(14)
	v_mul_f32_e32 v48, v48, v80
	ds_write_b32 v5, v48 offset:3072
	s_waitcnt vmcnt(12)
	v_mul_f32_e32 v49, v49, v81
	ds_write_b32 v5, v49 offset:3200
	s_waitcnt vmcnt(10)
	v_mul_f32_e32 v50, v50, v82
	ds_write_b32 v5, v50 offset:3328
	s_waitcnt vmcnt(8)
	v_mul_f32_e32 v51, v51, v83
	ds_write_b32 v5, v51 offset:3456
	s_waitcnt vmcnt(6)
	v_mul_f32_e32 v52, v52, v84
	ds_write_b32 v5, v52 offset:3584
	s_waitcnt vmcnt(4)
	v_mul_f32_e32 v53, v53, v85
	ds_write_b32 v5, v53 offset:3712
	s_waitcnt vmcnt(2)
	v_mul_f32_e32 v54, v54, v86
	ds_write_b32 v5, v54 offset:3840
	s_waitcnt vmcnt(0)
	v_mul_f32_e32 v55, v55, v87
	ds_write_b32 v5, v55 offset:3968
.LBB0_35:
	s_lshr_b32 s4, s33, 6
	s_lshl_b32 s5, s51, 3
	s_add_i32 s22, s5, s4
	s_lshl_b32 s34, s94, 3
	v_writelane_b32 v242, s4, 9
	s_cmpk_lt_i32 s22, 0x4000
	v_writelane_b32 v242, s5, 10
	s_cselect_b64 s[4:5], -1, 0
	s_ashr_i32 s23, s22, 31
	v_writelane_b32 v242, s4, 11
	s_and_b64 vcc, exec, s[4:5]
	v_mbcnt_lo_u32_b32 v146, -1, 0
	s_waitcnt lgkmcnt(0)
	s_barrier
	v_writelane_b32 v242, s5, 12
	s_cbranch_vccz .LBB0_42
	s_lshl_b64 s[4:5], s[22:23], 12
	v_ashrrev_i32_e32 v33, 31, v32
	s_add_u32 s4, s72, s4
	v_lshlrev_b64 v[0:1], 4, v[32:33]
	s_addc_u32 s5, s73, s5
	v_lshl_add_u64 v[2:3], s[4:5], 0, v[0:1]
	global_load_dwordx4 v[16:19], v[2:3], off offset:3072 nt
	global_load_dwordx4 v[20:23], v[2:3], off offset:2048 nt
	global_load_dwordx4 v[24:27], v[2:3], off offset:1024 nt
	global_load_dwordx4 v[28:31], v[2:3], off nt
	v_lshl_add_u64 v[34:35], s[72:73], 0, v[0:1]
	v_mbcnt_hi_u32_b32 v0, -1, v146
	v_and_b32_e32 v1, 64, v0
	v_add_u32_e32 v1, 64, v1
	v_xor_b32_e32 v2, 1, v0
	v_cmp_lt_i32_e32 vcc, v2, v1
	s_lshl_b64 s[16:17], s[22:23], 6
	s_ashr_i32 s35, s34, 31
	v_cndmask_b32_e32 v2, v0, v2, vcc
	v_lshlrev_b32_e32 v42, 2, v2
	v_xor_b32_e32 v2, 2, v0
	v_cmp_lt_i32_e32 vcc, v2, v1
	s_lshl_b64 s[18:19], s[22:23], 11
	v_cmp_gt_i32_e64 s[12:13], 16, v32
	v_cndmask_b32_e32 v2, v0, v2, vcc
	v_lshlrev_b32_e32 v43, 2, v2
	v_xor_b32_e32 v2, 4, v0
	v_cmp_lt_i32_e32 vcc, v2, v1
	v_lshl_add_u32 v48, v32, 4, 0
	v_lshl_add_u64 v[36:37], v[32:33], 2, s[16:17]
	v_cndmask_b32_e32 v2, v0, v2, vcc
	v_lshlrev_b32_e32 v44, 2, v2
	v_xor_b32_e32 v2, 8, v0
	v_cmp_lt_i32_e32 vcc, v2, v1
	s_lshl_b64 s[16:17], s[34:35], 6
	v_lshl_add_u64 v[38:39], v[32:33], 3, s[18:19]
	v_cndmask_b32_e32 v2, v0, v2, vcc
	v_lshlrev_b32_e32 v45, 2, v2
	v_xor_b32_e32 v2, 16, v0
	v_cmp_lt_i32_e32 vcc, v2, v1
	s_lshl_b64 s[18:19], s[34:35], 11
	s_mov_b32 s27, 0x1000000
	v_cndmask_b32_e32 v2, v0, v2, vcc
	v_lshlrev_b32_e32 v46, 2, v2
	v_xor_b32_e32 v2, 32, v0
	v_cmp_lt_i32_e32 vcc, v2, v1
	v_mov_b32_e32 v33, 0x358637bd
	s_mov_b32 s28, 0x800000
	v_cndmask_b32_e32 v0, v0, v2, vcc
	v_lshlrev_b32_e32 v47, 2, v0
	v_and_b32_e32 v0, 1, v32
	v_cmp_eq_u32_e64 s[4:5], 0, v0
	v_and_b32_e32 v0, 2, v32
	v_cmp_eq_u32_e64 s[6:7], 0, v0
	v_and_b32_e32 v0, 4, v32
	v_cmp_eq_u32_e64 s[8:9], 0, v0
	v_and_b32_e32 v0, 8, v32
	v_cmp_eq_u32_e64 s[10:11], 0, v0
	s_mov_b32 s29, s22
	s_branch .LBB0_38

.LBB0_362:
	v_readlane_b32 s4, v242, 8
	s_waitcnt lgkmcnt(0)
	s_barrier
	v_mbcnt_lo_u32_b32 v0, -1, 0
	v_mbcnt_hi_u32_b32 v0, -1, v0
	s_add_u32 s26, s92, 0x513600
	s_addc_u32 s27, s93, 0
	v_mov_b32_e32 v30, 0
	global_load_dword v32, v30, s[26:27] offset:0 sc1
	global_load_dword v33, v30, s[26:27] offset:256 sc1
	global_load_dword v34, v30, s[26:27] offset:512 sc1
	global_load_dword v35, v30, s[26:27] offset:768 sc1
	global_load_dword v36, v30, s[26:27] offset:1024 sc1
	global_load_dword v37, v30, s[26:27] offset:1280 sc1
	global_load_dword v38, v30, s[26:27] offset:1536 sc1
	global_load_dword v39, v30, s[26:27] offset:1792 sc1
	s_waitcnt vmcnt(0)
	v_mov_b32_e32 v26, -1
	v_mov_b32_e32 v27, 0
	v_min_u32_e32 v26, v26, v32
	v_add_u32_e32 v28, -1, v32
	v_and_b32_e32 v28, v28, v32
	v_or_b32_e32 v27, v27, v28
	v_min_u32_e32 v26, v26, v33
	v_add_u32_e32 v28, -1, v33
	v_and_b32_e32 v28, v28, v33
	v_or_b32_e32 v27, v27, v28
	v_min_u32_e32 v26, v26, v34
	v_add_u32_e32 v28, -1, v34
	v_and_b32_e32 v28, v28, v34
	v_or_b32_e32 v27, v27, v28
	v_min_u32_e32 v26, v26, v35
	v_add_u32_e32 v28, -1, v35
	v_and_b32_e32 v28, v28, v35
	v_or_b32_e32 v27, v27, v28
	v_min_u32_e32 v26, v26, v36
	v_add_u32_e32 v28, -1, v36
	v_and_b32_e32 v28, v28, v36
	v_or_b32_e32 v27, v27, v28
	v_min_u32_e32 v26, v26, v37
	v_add_u32_e32 v28, -1, v37
	v_and_b32_e32 v28, v28, v37
	v_or_b32_e32 v27, v27, v28
	v_min_u32_e32 v26, v26, v38
	v_add_u32_e32 v28, -1, v38
	v_and_b32_e32 v28, v28, v38
	v_or_b32_e32 v27, v27, v28
	v_min_u32_e32 v26, v26, v39
	v_add_u32_e32 v28, -1, v39
	v_and_b32_e32 v28, v28, v39
	v_or_b32_e32 v27, v27, v28
	v_cmp_ne_u32_e32 vcc, 0, v26
	s_nop 1
	v_cndmask_b32_e64 v26, 0, 1, vcc
	v_cmp_eq_u32_e32 vcc, 0, v27
	s_nop 1
	v_cndmask_b32_e32 v26, 0, v26, vcc
	v_mov_b32_e32 v27, 0x23ff8
	ds_write_b32 v27, v26
	s_mov_b32 s4, s40
	s_mov_b32 s5, s77
	v_and_b32_e32 v1, 15, v0
	v_lshrrev_b32_e32 v2, 4, v0
	s_lshr_b32 s38, s5, 1
	s_and_b32 s39, s5, 1
	s_lshr_b32 s7, s4, 2
	s_lshl_b32 s7, s7, 5
	s_and_b32 s8, s4, 3
	s_lshl_b32 s9, s7, 14
	s_add_u32 s10, s92, 0x9000000
	s_addc_u32 s11, s93, 0
	s_add_u32 s10, s10, s9
	s_addc_u32 s11, s11, 0
	s_add_u32 s12, s92, 0xb000000
	s_addc_u32 s13, s93, 0
	s_add_u32 s12, s12, s9
	s_addc_u32 s13, s13, 0
	s_add_u32 s14, s92, 0xd000000
	s_addc_u32 s15, s93, 0
	s_add_u32 s14, s14, s9
	s_addc_u32 s15, s15, 0
	s_lshl_b32 s26, s7, 13
	s_add_u32 s18, s92, 0xf000000
	s_addc_u32 s19, s93, 0
	s_add_u32 s18, s18, s26
	s_addc_u32 s19, s19, 0
	s_add_u32 s24, s90, 0x2000000
	s_addc_u32 s25, s91, 0
	s_add_u32 s24, s24, s9
	s_addc_u32 s25, s25, 0
	s_lshl_b32 s26, s8, 6
	s_add_u32 s24, s24, s26
	s_addc_u32 s25, s25, 0
	s_add_u32 s42, s92, 0x500000
	s_addc_u32 s43, s93, 0
	v_and_b32_e32 v26, 31, v0
	v_add_u32_e32 v26, s7, v26
	v_lshlrev_b32_e32 v26, 2, v26
	global_load_dword v24, v26, s[42:43]
	v_mov_b32_e32 v30, 0
	s_lshl_b32 s30, s5, 11
	s_lshl_b32 s31, s5, 10
	s_and_b32 s32, s5, 3
	s_lshl_b32 s32, s32, 10
	s_lshl_b32 s7, s5, 3
	v_add_u32_e32 v26, s7, v2
	v_and_b32_e32 v27, 15, v26
	v_xor_b32_e32 v27, v27, v1
	v_lshlrev_b32_e32 v27, 4, v27
	v_lshl_add_u32 v3, v26, 8, v27
	s_lshl_b32 s7, s5, 3
	s_add_u32 s7, s7, 4
	v_add_u32_e32 v26, s7, v2
	v_and_b32_e32 v27, 15, v26
	v_xor_b32_e32 v27, v27, v1
	v_lshlrev_b32_e32 v27, 4, v27
	v_lshl_add_u32 v4, v26, 8, v27
	v_lshrrev_b32_e32 v28, 3, v0
	v_and_b32_e32 v29, 7, v0
	s_lshl_b32 s7, s5, 4
	v_add_u32_e32 v26, s7, v28
	v_bfe_u32 v27, v26, 1, 3
	v_xor_b32_e32 v27, v27, v29
	v_lshlrev_b32_e32 v27, 4, v27
	v_lshl_add_u32 v5, v26, 7, v27
	s_lshl_b32 s7, s5, 4
	s_add_u32 s7, s7, 8
	v_add_u32_e32 v26, s7, v28
	v_bfe_u32 v27, v26, 1, 3
	v_xor_b32_e32 v27, v27, v29
	v_lshlrev_b32_e32 v27, 4, v27
	v_lshl_add_u32 v6, v26, 7, v27
	s_lshl_b32 s7, s5, 3
	v_add_u32_e32 v26, s7, v28
	v_bfe_u32 v27, v26, 1, 3
	v_xor_b32_e32 v27, v27, v29
	v_lshlrev_b32_e32 v27, 4, v27
	v_lshl_add_u32 v7, v26, 7, v27
	s_and_b32 s7, s5, 3
	s_lshl_b32 s7, s7, 4
	v_lshrrev_b32_e32 v26, 2, v0
	v_add_u32_e32 v26, s7, v26
	v_and_b32_e32 v27, 3, v0
	v_lshlrev_b32_e32 v27, 4, v27
	v_lshl_add_u32 v8, v26, 8, v27
	s_lshl_b32 s7, s39, 4
	v_add_u32_e32 v26, s7, v1
	s_lshl_b32 s8, s38, 4
	v_add_u32_e32 v27, s8, v1
	v_lshlrev_b32_e32 v28, 4, v2
	s_movk_i32 s9, 0x110
	v_mul_lo_u32 v29, v26, s9
	v_add_u32_e32 v10, v29, v28
	v_add_u32_e32 v10, 0x1c000, v10
	v_lshlrev_b32_e32 v31, 3, v2
	s_lshl_b32 s9, s38, 6
	v_add3_u32 v21, v29, v31, s9
	v_add_u32_e32 v21, 0x1c000, v21
	s_movk_i32 s9, 0x90
	v_mul_lo_u32 v29, v26, s9
	v_add_u32_e32 v19, v29, v28
	v_add_u32_e32 v19, 0x1e200, v19
	s_lshl_b32 s9, s38, 5
	v_add3_u32 v20, v29, v31, s9
	v_add_u32_e32 v20, 0x1e200, v20
	v_add_u32_e32 v29, 0, v2
	v_xor_b32_e32 v29, v29, v1
	v_lshlrev_b32_e32 v29, 4, v29
	v_lshl_add_u32 v11, v27, 8, v29
	v_add_u32_e32 v29, 4, v2
	v_xor_b32_e32 v29, v29, v1
	v_lshlrev_b32_e32 v29, 4, v29
	v_lshl_add_u32 v12, v27, 8, v29
	v_add_u32_e32 v29, 8, v2
	v_xor_b32_e32 v29, v29, v1
	v_lshlrev_b32_e32 v29, 4, v29
	v_lshl_add_u32 v13, v27, 8, v29
	v_add_u32_e32 v29, 12, v2
	v_xor_b32_e32 v29, v29, v1
	v_lshlrev_b32_e32 v29, 4, v29
	v_lshl_add_u32 v14, v27, 8, v29
	v_lshrrev_b32_e32 v31, 1, v1
	s_lshl_b32 s9, s38, 5
	v_add_u32_e32 v26, s9, v1
	v_add_u32_e32 v29, 0, v2
	v_xor_b32_e32 v29, v29, v31
	v_lshlrev_b32_e32 v29, 4, v29
	v_lshl_add_u32 v15, v26, 7, v29
	v_add_u32_e32 v15, 0x10000, v15
	v_lshl_add_u32 v17, v27, 7, v29
	v_add_u32_e32 v17, 0x18000, v17
	v_add_u32_e32 v29, 4, v2
	v_xor_b32_e32 v29, v29, v31
	v_lshlrev_b32_e32 v29, 4, v29
	v_lshl_add_u32 v16, v26, 7, v29
	v_add_u32_e32 v16, 0x10000, v16
	v_lshl_add_u32 v18, v27, 7, v29
	v_add_u32_e32 v18, 0x18000, v18
	s_lshl_b32 s9, s38, 10
	v_lshlrev_b32_e32 v29, 8, v2
	v_add_u32_e32 v29, s9, v29
	s_lshl_b32 s9, s39, 5
	v_lshl_add_u32 v29, v1, 1, v29
	v_add_u32_e32 v29, s9, v29
	v_add_u32_e32 v22, 0x1f400, v29
	v_lshlrev_b32_e32 v29, 3, v2
	v_lshl_add_u32 v29, v27, 8, v29
	v_add_u32_e32 v9, s9, v29
	v_mov_b32_e32 v32, 0
	v_mov_b32_e32 v33, 0
	v_mov_b32_e32 v34, 0
	v_mov_b32_e32 v35, 0
	v_lshl_add_u32 v26, s5, 6, v0
	v_lshlrev_b32_e32 v27, 4, v26
	v_add_u32_e32 v27, 0x1c000, v27
	ds_write_b128 v27, v[32:35]
	v_and_b32_e32 v26, 31, v26
	v_lshlrev_b32_e32 v27, 4, v26
	v_add_u32_e32 v27, 0x1e000, v27
	ds_write_b128 v27, v[32:35]
	v_mov_b32_e32 v92, 0
	v_mov_b32_e32 v93, 0
	v_mov_b32_e32 v94, 0
	v_mov_b32_e32 v95, 0
	v_mov_b32_e32 v96, 0
	v_mov_b32_e32 v97, 0
	v_mov_b32_e32 v98, 0
	v_mov_b32_e32 v99, 0
	s_mov_b32 s6, 0
	global_load_dword v25, v30, s[42:43]
	global_load_dword v25, v30, s[42:43]
	global_load_dword v25, v30, s[42:43]
	s_add_i32 m0, s32, 0x1f400
	s_nop 0
	global_load_lds_dwordx4 v8, s[24:25]
	s_add_i32 m0, s30, 0x0
	s_nop 0
	global_load_lds_dwordx4 v3, s[10:11]
	s_add_i32 m0, s30, 0x400
	s_nop 0
	global_load_lds_dwordx4 v4, s[10:11]
	s_add_i32 m0, s30, 0x8000
	s_nop 0
	global_load_lds_dwordx4 v3, s[12:13]
	s_add_i32 m0, s30, 0x8400
	s_nop 0
	global_load_lds_dwordx4 v4, s[12:13]
	global_load_dword v25, v30, s[42:43]
	s_add_i32 m0, s30, 0x10000
	s_nop 0
	global_load_lds_dwordx4 v5, s[14:15]
	s_add_i32 m0, s30, 0x10400
	s_nop 0
	global_load_lds_dwordx4 v6, s[14:15]
	s_add_i32 m0, s31, 0x18000
	s_nop 0
	global_load_lds_dwordx4 v7, s[18:19]
	s_add_u32 s26, s24, 0x4000
	s_addc_u32 s27, s25, 0
	s_add_i32 m0, s32, 0x20400
	s_nop 0
	global_load_lds_dwordx4 v8, s[26:27]
	s_add_u32 s26, s10, 0x4000
	s_addc_u32 s27, s11, 0
	s_add_i32 m0, s30, 0x4000
	s_nop 0
	global_load_lds_dwordx4 v3, s[26:27]
	s_add_i32 m0, s30, 0x4400
	s_nop 0
	global_load_lds_dwordx4 v4, s[26:27]
	s_add_u32 s26, s12, 0x4000
	s_addc_u32 s27, s13, 0
	s_add_i32 m0, s30, 0xc000
	s_nop 0
	global_load_lds_dwordx4 v3, s[26:27]
	s_add_i32 m0, s30, 0xc400
	s_nop 0
	global_load_lds_dwordx4 v4, s[26:27]
	global_load_dword v25, v30, s[42:43]
	s_waitcnt vmcnt(10) lgkmcnt(0)
	s_barrier

.LBB0_722:
	s_andn2_saveexec_b64 s[4:5], s[8:9]
	s_cbranch_execz .LBB0_742
	v_mov_b32_e32 v1, 0x23ff8
	ds_read_b32 v1, v1
	s_waitcnt lgkmcnt(0)
	v_readfirstlane_b32 s3, v1
	s_nop 0
	s_cmp_lg_u32 s3, 0
	s_cbranch_scc1 .Lxloc_0
	s_mov_b64 s[8:9], exec
	buffer_wbl2 sc1
	s_waitcnt lgkmcnt(0)
	s_waitcnt vmcnt(0)
	v_mbcnt_lo_u32_b32 v1, s8, 0
	v_mbcnt_hi_u32_b32 v1, s9, v1
	v_cmp_eq_u32_e32 vcc, 0, v1
	s_and_saveexec_b64 s[10:11], vcc
	s_cbranch_execz .LBB0_725
	s_bcnt1_i32_b64 s3, s[8:9]
	v_readlane_b32 s4, v240, 24
	v_mov_b32_e32 v2, 0
	v_mov_b32_e32 v3, s3
	v_readlane_b32 s5, v240, 25
	s_nop 4
	global_atomic_add v2, v2, v3, s[4:5] sc0

.LBB0_805:
	s_andn2_saveexec_b64 s[4:5], s[6:7]
	s_cbranch_execz .LBB0_825
	v_mov_b32_e32 v1, 0x23ff8
	ds_read_b32 v1, v1
	s_waitcnt lgkmcnt(0)
	v_readfirstlane_b32 s3, v1
	s_nop 0
	s_cmp_lg_u32 s3, 0
	s_cbranch_scc1 .Lxloc_1
	s_mov_b64 s[6:7], exec
	buffer_wbl2 sc1
	s_waitcnt lgkmcnt(0)
	s_waitcnt vmcnt(0)
	v_mbcnt_lo_u32_b32 v1, s6, 0
	v_mbcnt_hi_u32_b32 v1, s7, v1
	v_cmp_eq_u32_e32 vcc, 0, v1
	s_and_saveexec_b64 s[8:9], vcc
	s_cbranch_execz .LBB0_808
	s_bcnt1_i32_b64 s3, s[6:7]
	v_readlane_b32 s4, v240, 24
	v_mov_b32_e32 v2, 0
	v_mov_b32_e32 v3, s3
	v_readlane_b32 s5, v240, 25
	s_nop 4
	global_atomic_add v2, v2, v3, s[4:5] sc0
